# combined: peel + pipelined cast_rows + idx head-weight load overlap + shifted bias tables with far-tile C=0 QK paths
# baseline (speedup 1.0000x reference)
; __device__ __forceinline__ void idx_unit(unsigned char* lds, const bf16_t* P, int b, int qb16, unsigned* bits) {
;     ...
;     const int t0 = qb16 * 16; const size_t tokb = (size_t)b * SEQ, tok0 = tokb + t0;
;     const int nscan = ((t0 + 16 + 511) >> 9) << 9;
;     const int ncomp = ((t0 + 16 + 31) / 32);
;     const int nblk = ncomp;
;     if (tid < 128) wl[tid] = bf2f(P[(tok0 + (tid >> 3)) * PW + P_IW + (tid & 7)]) * (0.35355339059327373f * 0.125f);
;     bf16x8 aq[4][4];
; #pragma unroll
;     for (int rb = 0; rb < 4; ++rb) { const bf16_t* ap = P + (tok0 + rb * 4 + (r32 >> 3)) * PW + P_IQ + (r32 & 7) * 64 + 8 * hi;
; #pragma unroll
;         for (int kk = 0; kk < 4; ++kk) aq[rb][kk] = *(const bf16x8*)(ap + kk * 16); }
;     __syncthreads();
;     f32x4 wreg[16];
; #pragma unroll
;     for (int q = 0; q < 16; ++q) wreg[q] = *(const f32x4*)(wl + q * 8 + 4 * hi);
;     bf16x8 bk[4], bn[4];
;     { const bf16_t* kp = P + (tokb + (wid < nblk ? wid : 0) * 32 + r32) * PW + P_IK + 8 * hi;
; #pragma unroll
;       for (int kk = 0; kk < 4; ++kk) { bk[kk] = *(const bf16x8*)(kp + kk * 16); bn[kk] = bk[kk]; } }
.LBB0_394:
	s_and_b32 s8, s76, -16
	s_bitcmp1_b32 s76, 8
	s_cselect_b32 s0, 0xf0, 0
	s_xor_b32 s8, s8, s0
	s_lshl_b32 s0, s76, 12
	s_and_b32 s64, s0, 0xf000
	s_ashr_i32 s0, s8, 31
	s_add_u32 s70, s64, s8
	v_mov_b32_e32 v182, v228
	s_addc_u32 s71, 0, s0
	s_movk_i32 s0, 0x80
	s_nop 0
	v_readfirstlane_b32 s4, v182
	v_cmp_gt_i32_e32 vcc, s0, v182
	s_and_saveexec_b64 s[0:1], vcc
	s_cbranch_execz .LBB0_396
	v_ashrrev_i32_e32 v2, 3, v182
	v_ashrrev_i32_e32 v3, 31, v2
	v_lshl_add_u64 v[2:3], s[70:71], 0, v[2:3]
	v_mov_b64_e32 v[4:5], s[46:47]
	v_and_b32_e32 v0, 7, v182
	v_mad_u64_u32 v[4:5], s[6:7], v2, s37, v[4:5]
	v_mad_i32_i24 v5, v3, s37, v5
	v_lshlrev_b32_e32 v0, 1, v0
	v_lshl_add_u64 v[2:3], v[4:5], 0, v[0:1]
	v_add_co_u32_e32 v2, vcc, 0x1000, v2
	s_nop 1
	v_addc_co_u32_e32 v3, vcc, 0, v3, vcc
	global_load_ushort v226, v[2:3], off offset:1152
	v_lshl_add_u32 v227, v182, 2, 0
	v_add_u32_e32 v227, 0x20000, v227
.LBB0_396:
	s_or_b64 exec, exec, s[0:1]
	v_bfe_u32 v0, v182, 3, 2
	v_or_b32_e32 v3, s70, v0
	v_mov_b64_e32 v[4:5], s[46:47]
	v_mad_u64_u32 v[6:7], s[0:1], v3, s37, v[4:5]
	v_lshlrev_b32_e32 v0, 7, v182
	v_bfe_u32 v2, v182, 5, 1
	v_mad_i32_i24 v7, s71, v236, v7
	v_and_b32_e32 v0, 0x380, v0
	v_lshl_add_u64 v[6:7], v[6:7], 0, v[0:1]
	v_lshlrev_b32_e32 v8, 4, v2
	v_mov_b32_e32 v9, v1
	v_lshl_add_u64 v[6:7], v[6:7], 0, v[8:9]
	s_mov_b64 s[10:11], 0x1000
	s_movk_i32 s6, 0x1000
	v_lshl_add_u64 v[10:11], v[6:7], 0, s[10:11]
	v_add_co_u32_e32 v6, vcc, s6, v6
	s_movk_i32 s5, 0x1000
	s_nop 0
	v_addc_co_u32_e32 v7, vcc, 0, v7, vcc
	global_load_dwordx4 v[18:21], v[10:11], off offset:32
	global_load_dwordx4 v[22:25], v[10:11], off offset:64
	global_load_dwordx4 v[26:29], v[6:7], off
	global_load_dwordx4 v[30:33], v[10:11], off offset:96
	v_or_b32_e32 v6, 4, v3
	v_mad_u64_u32 v[6:7], s[0:1], v6, s37, v[4:5]
	v_mad_i32_i24 v7, s71, v236, v7
	v_lshl_add_u64 v[6:7], v[6:7], 0, v[0:1]
	v_lshl_add_u64 v[6:7], v[6:7], 0, v[8:9]
	v_lshl_add_u64 v[10:11], v[6:7], 0, s[10:11]
	v_add_co_u32_e32 v6, vcc, s6, v6
	v_and_b32_e32 v178, 31, v182
	s_nop 0
	v_addc_co_u32_e32 v7, vcc, 0, v7, vcc
	global_load_dwordx4 v[34:37], v[10:11], off offset:32
	global_load_dwordx4 v[38:41], v[10:11], off offset:64
	global_load_dwordx4 v[42:45], v[6:7], off
	global_load_dwordx4 v[46:49], v[10:11], off offset:96
	v_or_b32_e32 v6, 8, v3
	v_mad_u64_u32 v[6:7], s[0:1], v6, s37, v[4:5]
	v_mad_i32_i24 v7, s71, v236, v7
	v_or_b32_e32 v3, 12, v3
	v_lshl_add_u64 v[6:7], v[6:7], 0, v[0:1]
	v_mad_u64_u32 v[4:5], s[0:1], v3, s37, v[4:5]
	v_lshl_add_u64 v[6:7], v[6:7], 0, v[8:9]
	v_mad_i32_i24 v5, s71, v236, v5
	v_lshl_add_u64 v[10:11], v[6:7], 0, s[10:11]
	v_add_co_u32_e32 v6, vcc, s6, v6
	v_lshl_add_u64 v[4:5], v[4:5], 0, v[0:1]
	s_nop 0
	v_addc_co_u32_e32 v7, vcc, 0, v7, vcc
	v_lshl_add_u64 v[4:5], v[4:5], 0, v[8:9]
	global_load_dwordx4 v[50:53], v[10:11], off offset:32
	global_load_dwordx4 v[54:57], v[10:11], off offset:64
	global_load_dwordx4 v[58:61], v[6:7], off
	global_load_dwordx4 v[62:65], v[10:11], off offset:96
	v_lshl_add_u64 v[6:7], v[4:5], 0, s[10:11]
	v_add_co_u32_e32 v4, vcc, 0x1000, v4
	s_add_i32 s0, s8, 47
	s_nop 0
	v_addc_co_u32_e32 v5, vcc, 0, v5, vcc
	global_load_dwordx4 v[66:69], v[6:7], off offset:32
	global_load_dwordx4 v[70:73], v[6:7], off offset:64
	global_load_dwordx4 v[74:77], v[4:5], off
	global_load_dwordx4 v[78:81], v[6:7], off offset:96
	v_cmp_gt_i32_e32 vcc, 0x80, v182
	s_and_saveexec_b64 s[6:7], vcc
	s_cbranch_execz .Lwl_skip
	s_waitcnt vmcnt(16)
	v_lshlrev_b32_e32 v226, 16, v226
	v_mul_f32_e32 v226, 0x3d3504f3, v226
	ds_write_b32 v227, v226
.Lwl_skip:
	s_or_b64 exec, exec, s[6:7]
	s_ashr_i32 s1, s0, 31
	s_lshr_b32 s1, s1, 27
	s_add_i32 s0, s0, s1
	s_ashr_i32 s10, s4, 6
	s_ashr_i32 s9, s0, 5
	s_cmp_ge_i32 s10, s9
	v_mov_b32_e32 v179, v1
	s_waitcnt lgkmcnt(0)
	s_barrier
	s_cbranch_scc1 .LBB0_409
	s_lshl_b32 s6, s10, 5
	s_add_i32 s0, s6, s64
	v_lshlrev_b32_e32 v0, 3, v2
	v_or_b32_e32 v3, s0, v178
	v_mov_b64_e32 v[4:5], s[46:47]
	v_mad_i64_i32 v[4:5], s[0:1], v3, s37, v[4:5]
	v_lshlrev_b32_e32 v0, 1, v0
	v_lshl_add_u64 v[4:5], v[4:5], 0, v[0:1]
	s_mov_b64 s[0:1], 0x1400
	v_lshl_add_u64 v[6:7], v[4:5], 0, s[0:1]
	v_add_co_u32_e32 v4, vcc, s5, v4
	global_load_dwordx4 v[162:165], v[6:7], off offset:96
	global_load_dwordx4 v[166:169], v[6:7], off offset:64
	global_load_dwordx4 v[170:173], v[6:7], off offset:32
	v_addc_co_u32_e32 v5, vcc, 0, v5, vcc
	global_load_dwordx4 v[174:177], v[4:5], off offset:1024
	v_lshl_add_u32 v3, v2, 4, 0
	v_add_u32_e32 v3, 0x20000, v3
	ds_read_b128 v[82:85], v3 offset:480
	ds_read_b128 v[86:89], v3 offset:448
	ds_read_b128 v[90:93], v3 offset:416
	ds_read_b128 v[94:97], v3 offset:384
	ds_read_b128 v[98:101], v3 offset:352
	ds_read_b128 v[102:105], v3 offset:320
	ds_read_b128 v[106:109], v3 offset:288
	ds_read_b128 v[110:113], v3 offset:256
	ds_read_b128 v[114:117], v3 offset:224
	ds_read_b128 v[118:121], v3 offset:192
	ds_read_b128 v[122:125], v3 offset:160
	ds_read_b128 v[126:129], v3 offset:128
	ds_read_b128 v[130:133], v3 offset:96
	ds_read_b128 v[134:137], v3 offset:64
	ds_read_b128 v[138:141], v3
	ds_read_b128 v[142:145], v3 offset:32
	s_lshl_b32 s0, s10, 6
	v_cmp_eq_u32_e64 s[4:5], 0, v2
	v_lshl_or_b32 v183, v2, 1, s8
	v_lshl_add_u32 v2, v2, 14, s0
	s_add_i32 s1, 0, 0x10000
	v_lshl_or_b32 v2, v178, 1, v2
	v_or_b32_e32 v184, 1, v183
	v_or_b32_e32 v185, 4, v183
	v_or_b32_e32 v187, 5, v183
	v_or_b32_e32 v192, 8, v183
	v_or_b32_e32 v193, 9, v183
	v_or_b32_e32 v194, 12, v183
	v_or_b32_e32 v195, 13, v183
	v_or_b32_e32 v180, s6, v178
	v_add_u32_e32 v196, s1, v2
	s_mov_b32 s101, 0x8000
	v_add_u32_e32 v197, 0xffff0000, v196
	s_waitcnt vmcnt(3)
	v_mov_b64_e32 v[154:155], v[162:163]
	s_waitcnt vmcnt(2)
	v_mov_b64_e32 v[146:147], v[166:167]
	s_waitcnt vmcnt(1)
	v_mov_b64_e32 v[150:151], v[170:171]
	v_mov_b64_e32 v[156:157], v[164:165]
	v_mov_b64_e32 v[148:149], v[168:169]
	s_waitcnt vmcnt(0)
	v_mov_b64_e32 v[158:159], v[174:175]
	v_mov_b64_e32 v[152:153], v[172:173]
	v_mov_b64_e32 v[160:161], v[176:177]
	s_branch .Lidx_pro
